# down GEMMs: third-round tiles cut 4 ways along K over 128 workgroups, f32 partials via ws, owner adds in fixed order then runs epilogue
# speedup vs baseline: 1.0284x; 1.0207x over previous
; #define PG8_STAGE(bufoff, gbase, voff) do { _Pragma("unroll") for (int _i = 0; _i < 2; ++_i) \
;         __builtin_amdgcn_global_load_lds((const unsigned*)((const char*)(gbase) + (voff)[_i]), (PG8_LAS unsigned*)(lds + (bufoff) + ldsw + _i * 8192), 16, 0, 0); } while (0)
; #define PG8_WAIT_V(n) asm volatile("s_waitcnt vmcnt(" #n ")" ::: "memory")
; #define PG8_BAR __builtin_amdgcn_s_barrier()
; template <class Epi, class Sched, bool ALIGN_EPI = false, bool SP2 = false>
; __device__ __forceinline__ void gemm_phase(PG8_LAS unsigned char* lds, const Gemm g, const Sched& S, const Epi& E) {
;     ...
;     const char* cA = (const char*)g.A + (size_t)cur.pm * tstep + (size_t)cur.kt0 * kstepA; const char* cB = (const char*)g.Bt + (size_t)cur.pn * tstep + (size_t)cur.kt0 * kstep;
;     S.a_ready(cur);
;     if constexpr (SP2) {
;         PG8_STAGE(PG8_SB(0, 0), cB, voffB); PG8_STAGE(PG8_SB(0, 1), cB + hstep, voffB); PG8_STAGE(PG8_SA(0, 0), cA, voffA); PG8_STAGE(PG8_SA(0, 1), cA + hstepA, voffA);
;         if (wr == 1) PG8_BAR;
;         PG8_WAIT_V(2); PG8_BAR;
;         PG8_STAGE(PG8_SB(1, 0), cB + kstep, voffB); PG8_STAGE(PG8_SA(1, 0), cA + kstepA, voffA); PG8_STAGE(PG8_SB(1, 1), cB + hstep + kstep, voffB);
;         PG8_WAIT_V(6); PG8_BAR;
;     } else {
;         PG8_STAGE(PG8_SB(0, 0), cB, voffB); PG8_STAGE(PG8_SA(0, 0), cA, voffA); PG8_STAGE(PG8_SB(0, 1), cB + hstep, voffB); PG8_STAGE(PG8_SA(0, 1), cA + hstepA, voffA);
;         if (wr == 1) PG8_BAR;
;         PG8_WAIT_V(4); PG8_BAR;
;         PG8_STAGE(PG8_SB(1, 0), cB + kstep, voffB); PG8_STAGE(PG8_SA(1, 0), cA + kstepA, voffA); PG8_STAGE(PG8_SB(1, 1), cB + hstep + kstep, voffB);
;         PG8_WAIT_V(6); PG8_BAR;
;     }
.LBB0_439:
	s_and_b64 s[16:17], s[4:5], exec
	s_cselect_b32 s38, 7, 15
	s_lshr_b32 s39, s15, 6
	s_and_b64 s[16:17], s[4:5], exec
	s_movk_i32 s15, 0x1400
	s_cselect_b32 s16, s15, 0x2000
	s_movk_i32 s15, 0x80
	s_cselect_b32 s40, s15, 0x8000
	s_lshl_b32 s13, s13, 5
	s_and_b32 s44, s13, 0x60
	s_add_i32 m0, s34, 0x18000
	v_lshl_add_u64 v[0:1], v[0:1], 0, s[80:81]
	s_lshl_b32 s41, s14, 6
	s_lshl_b32 s17, s14, 13
	s_lshl_b32 s13, s44, 7
	s_waitcnt vmcnt(2)
	s_barrier
	global_load_lds_dwordx4 v[0:1], off
	s_add_i32 m0, s34, 0x1a000
	s_add_u32 s14, s18, s40
	v_mov_b32_e32 v181, v161
	v_lshl_add_u64 v[0:1], v[2:3], 0, s[80:81]
	s_addc_u32 s15, s19, 0
	s_add_i32 s45, s34, 0x8000
	v_mov_b32_e32 v177, v161
	global_load_lds_dwordx4 v[0:1], off
	v_lshl_add_u64 v[0:1], s[14:15], 0, v[180:181]
	s_mov_b32 m0, s45
	s_add_i32 s52, s34, 0xa000
	global_load_lds_dwordx4 v[0:1], off
	v_lshl_add_u64 v[0:1], s[14:15], 0, v[176:177]
	s_mov_b32 m0, s52
	v_bfe_u32 v208, v8, 4, 2
	global_load_lds_dwordx4 v[0:1], off
	s_add_i32 m0, s34, 0x1c000
	v_lshl_add_u64 v[0:1], v[4:5], 0, s[80:81]
	global_load_lds_dwordx4 v[0:1], off
	v_lshl_add_u64 v[0:1], v[6:7], 0, s[80:81]
	s_add_i32 m0, s34, 0x1e000
	v_and_b32_e32 v173, 15, v8
	global_load_lds_dwordx4 v[0:1], off
	v_lshlrev_b32_e32 v0, 4, v208
	v_lshlrev_b32_e32 v1, 2, v8
	v_lshl_or_b32 v0, v173, 6, v0
	v_and_b32_e32 v1, 32, v1
	s_cmpk_lt_u32 s12, 0x100
	v_cndmask_b32_e64 v182, 0.5, 1.0, s[4:5]
	v_bitop3_b32 v209, v0, s13, v1 bitop3:0xde
	s_cselect_b64 s[12:13], -1, 0
	s_and_b64 s[4:5], s[6:7], exec
	s_cselect_b32 s4, 0x800, s16
	s_waitcnt vmcnt(6)
	s_lshl_b32 s4, s4, 2
	v_readlane_b32 s6, v255, 35
	v_bitop3_b32 v2, v0, s17, v1 bitop3:0xde
	v_readlane_b32 s7, v255, 36
	s_add_u32 s67, s6, s4
	s_mov_b32 s65, 0
	s_addc_u32 s68, s7, 0
	s_mov_b32 s101, 0
	v_mov_b32_e32 v184, v182
	v_mov_b32_e32 v185, v182
	v_add_u32_e32 v210, 0, v2
	v_readlane_b32 s43, v254, 46
	v_readlane_b32 s42, v254, 44
	s_barrier
	s_branch .LBB0_442

;     __host__ __device__ bool next(int i, Unit& u) const {
;         const long L = (long)i * G + c; if (L >= nwg) return false;
;         int wgid = (int)L; { const int q = nwg / NXCD, r = nwg % NXCD, xcd = wgid % NXCD, off = wgid / NXCD; wgid = (xcd < r ? xcd * (q + 1) : r * (q + 1) + (xcd - r) * q) + off; }
;         const int nig = WGM * nN, gid = wgid / nig, fm = gid * WGM, gsz = (nM - fm) < WGM ? (nM - fm) : WGM;
;         u.pm = fm + ((wgid % nig) % gsz); u.pn = (wgid % nig) / gsz; u.kt0 = 0; u.nkt = nt; u.aux = 0; return true;
;     }
; template <class Epi, class Sched, bool ALIGN_EPI = false, bool SP2 = false>
; __device__ __forceinline__ void gemm_phase(PG8_LAS unsigned char* lds, const Gemm g, const Sched& S, const Epi& E) {
;     ...
;         const bool has_next = S.next(ui + 1, nxt);
;         const char* nA = has_next ? (const char*)g.A + (size_t)nxt.pm * tstep + (size_t)nxt.kt0 * kstepA : cA; const char* nB = has_next ? (const char*)g.Bt + (size_t)nxt.pn * tstep + (size_t)nxt.kt0 * kstep : cB;
;         const int nt = cur.nkt;
.LBB0_441:
	s_andn2_b64 vcc, exec, s[4:5]
	s_mov_b32 s43, s69
	s_mov_b32 s42, s78
	s_mov_b64 s[20:21], s[16:17]
	s_mov_b64 s[18:19], s[14:15]
	s_mov_b32 s101, s100
	s_cmp_eq_u32 s100, 0
	s_cbranch_scc1 .Lsk_cur_done
	s_and_b32 s2, s100, 3
	s_cmp_eq_u32 s2, 3
	s_cselect_b32 s39, 14, 10
.Lsk_cur_done:
	s_cbranch_vccz .LBB0_647
.LBB0_442:
	s_add_i32 s65, s65, 1
	v_readlane_b32 s2, v255, 42
	s_mul_i32 s4, s65, s2
	s_mul_hi_u32 s5, s65, s92
	s_add_i32 s5, s5, s4
	s_mul_i32 s4, s65, s92
	v_readlane_b32 s2, v255, 18
	s_add_u32 s4, s4, s2
	v_readlane_b32 s2, v255, 41
	s_addc_u32 s5, s5, s2
	s_mov_b32 s100, 0
	s_cmp_lg_u32 s65, 2
	s_cbranch_scc1 .Lsk_sched_done
	s_cmp_eq_u32 s77, 8
	s_cbranch_scc1 .Lsk_sched_done
	s_cmpk_lg_i32 s92, 0x100
	s_cbranch_scc1 .Lsk_sched_done
	v_readlane_b32 s2, v255, 18
	s_mov_b32 s4, 0x7fffffff
	s_mov_b32 s5, 0
	s_cmpk_gt_u32 s2, 0x7f
	s_cbranch_scc1 .Lsk_sched_done
	s_lshr_b32 s4, s2, 2
	s_lshl_b32 s100, s4, 8
	s_addk_i32 s4, 0x200
	s_and_b32 s2, s2, 3
	s_or_b32 s100, s100, s2
	s_bitset1_b32 s100, 16
.Lsk_sched_done:
	v_cmp_gt_i64_e32 vcc, s[4:5], v[166:167]
	v_cmp_lt_i64_e64 s[6:7], s[4:5], v[164:165]
	s_cbranch_vccnz .LBB0_444
	s_ashr_i32 s5, s4, 31
	s_lshr_b32 s5, s5, 29
	s_add_i32 s5, s4, s5
	s_ashr_i32 s14, s5, 3
	s_and_b32 s5, s5, -8
	s_sub_i32 s4, s4, s5
	s_cmp_lt_i32 s4, 0
	s_movk_i32 s2, 0x45
	s_cselect_b32 s5, s2, 0x44
	s_mul_i32 s4, s4, s5
	s_add_i32 s4, s4, s14
	s_ashr_i32 s5, s4, 31
	s_lshr_b32 s5, s5, 27
	s_add_i32 s5, s4, s5
	s_ashr_i32 s14, s5, 5
	s_lshl_b32 s14, s14, 3
	s_sub_i32 s15, 0x88, s14
	s_min_i32 s15, s15, 8
	s_abs_i32 s16, s15
	v_cvt_f32_u32_e32 v0, s16
	s_sub_i32 s22, 0, s16
	s_andn2_b32 s5, s5, 31
	s_sub_i32 s4, s4, s5
	v_rcp_iflag_f32_e32 v0, v0
	s_abs_i32 s5, s4
	s_xor_b32 s17, s4, s15
	s_ashr_i32 s17, s17, 31
	v_mul_f32_e32 v0, 0x4f7ffffe, v0
	v_cvt_u32_f32_e32 v0, v0
	s_nop 0
	v_readfirstlane_b32 s23, v0
	s_mul_i32 s22, s22, s23
	s_mul_hi_u32 s22, s23, s22
	s_add_i32 s23, s23, s22
	s_mul_hi_u32 s22, s5, s23
	s_mul_i32 s23, s22, s16
	s_sub_i32 s5, s5, s23
	s_add_i32 s66, s22, 1
	s_sub_i32 s23, s5, s16
	s_cmp_ge_u32 s5, s16
	s_cselect_b32 s22, s66, s22
	s_cselect_b32 s5, s23, s5
	s_add_i32 s23, s22, 1
	s_cmp_ge_u32 s5, s16
	s_cselect_b32 s5, s23, s22
	s_xor_b32 s5, s5, s17
	s_sub_i32 s69, s5, s17
	s_mul_i32 s5, s69, s15
	s_sub_i32 s4, s4, s5
	s_add_i32 s78, s14, s4

; template <class Epi, class Sched, bool ALIGN_EPI = false, bool SP2 = false>
; __device__ __forceinline__ void gemm_phase(PG8_LAS unsigned char* lds, const Gemm g, const Sched& S, const Epi& E) {
;     ...
;         const bool has_next = S.next(ui + 1, nxt);
;         const char* nA = has_next ? (const char*)g.A + (size_t)nxt.pm * tstep + (size_t)nxt.kt0 * kstepA : cA; const char* nB = has_next ? (const char*)g.Bt + (size_t)nxt.pn * tstep + (size_t)nxt.kt0 * kstep : cB;
.LBB0_448:
	s_cmp_eq_u32 s100, 0
	s_cbranch_scc1 .Lsk_ptr_done
	s_and_b32 s2, s100, 3
	s_mul_i32 s22, s2, 10
	s_lshl_b32 s23, s22, 15
	s_add_u32 s14, s14, s23
	s_addc_u32 s15, s15, 0
	s_lshl_b32 s23, s22, 7
	s_add_u32 s16, s16, s23
	s_addc_u32 s17, s17, 0

; #define PG8_BAR __builtin_amdgcn_s_barrier()
; template <class Epi, class Sched, bool ALIGN_EPI = false, bool SP2 = false>
; __device__ __forceinline__ void gemm_phase(PG8_LAS unsigned char* lds, const Gemm g, const Sched& S, const Epi& E) {
;     ...
;         if constexpr (ALIGN_EPI) { if (wr == 0) PG8_BAR; }
;         if constexpr (!Epi::AFTER_DRAIN) { E(acc, cur, wr, wc, fr, fq); S.done(cur); }
;         if (!has_next) break;
.LBB0_452:
	s_cmp_eq_u32 s101, 0
	s_cbranch_scc1 .Lsk_epi_normal
	v_readlane_b32 s6, v255, 49
	v_readlane_b32 s84, v255, 37
	v_readlane_b32 s85, v255, 38
	v_readlane_b32 s86, v255, 29
	v_readlane_b32 s87, v255, 30
	s_bfe_u32 s7, s101, 0x50008
	s_and_b32 s22, s101, 3
	v_and_b32_e32 v186, 63, v194
	v_lshlrev_b32_e32 v186, 4, v186
	s_lshl_b32 s23, s7, 8
	s_movk_i32 s2, 0x4000
	s_cmp_eq_u32 s77, 3
	s_cselect_b32 s2, 0x2000, s2
	s_add_i32 s23, s23, s2
	s_add_u32 s86, s86, s23
	s_addc_u32 s87, s87, 0
	s_mul_i32 s23, s7, 3
	s_lshl_b32 s6, s6, 15
	s_cmp_eq_u32 s22, 3
	s_cbranch_scc1 .Lsk_owner
	s_add_i32 s23, s23, s22
	s_lshl_b32 s23, s23, 18
	s_add_i32 s23, s23, s6
	s_add_u32 s84, s84, s23
	s_addc_u32 s85, s85, 0
	global_store_dwordx4 v186, v[0:3], s[84:85]
	global_store_dwordx4 v186, v[4:7], s[84:85] offset:1024
	global_store_dwordx4 v186, v[8:11], s[84:85] offset:2048
	global_store_dwordx4 v186, v[12:15], s[84:85] offset:3072
	s_add_u32 s84, s84, 0x1000
	s_addc_u32 s85, s85, 0
	global_store_dwordx4 v186, v[16:19], s[84:85]
	global_store_dwordx4 v186, v[20:23], s[84:85] offset:1024
	global_store_dwordx4 v186, v[24:27], s[84:85] offset:2048
	global_store_dwordx4 v186, v[28:31], s[84:85] offset:3072
	s_add_u32 s84, s84, 0x1000
	s_addc_u32 s85, s85, 0
	global_store_dwordx4 v186, v[32:35], s[84:85]
	global_store_dwordx4 v186, v[36:39], s[84:85] offset:1024
	global_store_dwordx4 v186, v[40:43], s[84:85] offset:2048
	global_store_dwordx4 v186, v[44:47], s[84:85] offset:3072
	s_add_u32 s84, s84, 0x1000
	s_addc_u32 s85, s85, 0
	global_store_dwordx4 v186, v[48:51], s[84:85]
	global_store_dwordx4 v186, v[52:55], s[84:85] offset:1024
	global_store_dwordx4 v186, v[56:59], s[84:85] offset:2048
	global_store_dwordx4 v186, v[60:63], s[84:85] offset:3072
	s_add_u32 s84, s84, 0x1000
	s_addc_u32 s85, s85, 0
	global_store_dwordx4 v186, v[64:67], s[84:85]
	global_store_dwordx4 v186, v[68:71], s[84:85] offset:1024
	global_store_dwordx4 v186, v[72:75], s[84:85] offset:2048
	global_store_dwordx4 v186, v[76:79], s[84:85] offset:3072
	s_add_u32 s84, s84, 0x1000
	s_addc_u32 s85, s85, 0
	global_store_dwordx4 v186, v[80:83], s[84:85]
	global_store_dwordx4 v186, v[84:87], s[84:85] offset:1024
	global_store_dwordx4 v186, v[88:91], s[84:85] offset:2048
	global_store_dwordx4 v186, v[92:95], s[84:85] offset:3072
	s_add_u32 s84, s84, 0x1000
	s_addc_u32 s85, s85, 0
	global_store_dwordx4 v186, v[96:99], s[84:85]
	global_store_dwordx4 v186, v[100:103], s[84:85] offset:1024
	global_store_dwordx4 v186, v[104:107], s[84:85] offset:2048
	global_store_dwordx4 v186, v[108:111], s[84:85] offset:3072
	s_add_u32 s84, s84, 0x1000
	s_addc_u32 s85, s85, 0
	global_store_dwordx4 v186, v[112:115], s[84:85]
	global_store_dwordx4 v186, v[116:119], s[84:85] offset:1024
	global_store_dwordx4 v186, v[120:123], s[84:85] offset:2048
	global_store_dwordx4 v186, v[124:127], s[84:85] offset:3072
	s_waitcnt vmcnt(0)
	s_barrier
	s_cmp_lg_u32 s6, 0
	s_cbranch_scc1 .Lsk_pub_done
	buffer_wbl2 sc1
	s_waitcnt vmcnt(0)
	s_mov_b64 s[22:23], exec
	s_mov_b64 exec, 1
	global_atomic_add v161, v196, s[86:87]
	s_mov_b64 exec, s[22:23]
	s_waitcnt vmcnt(0)
.Lsk_pub_done:
	s_mov_b64 s[4:5], -1
	s_branch .LBB0_441
.Lsk_owner:
	s_lshl_b32 s23, s23, 18
	s_add_i32 s23, s23, s6
	s_add_u32 s84, s84, s23
	s_addc_u32 s85, s85, 0
	s_mov_b32 s22, 0
.Lsk_poll:
	global_load_dword v187, v161, s[86:87] sc1
	s_waitcnt vmcnt(0)
	v_readfirstlane_b32 s2, v187
	s_add_i32 s22, s22, 1
	s_cmp_ge_u32 s2, 3
	s_cbranch_scc1 .Lsk_ready
	s_cmp_gt_u32 s22, 0x40000
	s_cbranch_scc1 .Lsk_ready
	s_sleep 2
	s_branch .Lsk_poll
.Lsk_ready:
	buffer_inv sc1
	s_waitcnt vmcnt(0)
	global_load_dwordx4 v[128:131], v186, s[84:85]
	global_load_dwordx4 v[132:135], v186, s[84:85] offset:1024
	global_load_dwordx4 v[136:139], v186, s[84:85] offset:2048
	global_load_dwordx4 v[140:143], v186, s[84:85] offset:3072
	s_add_u32 s84, s84, 0x1000
	s_addc_u32 s85, s85, 0
	global_load_dwordx4 v[144:147], v186, s[84:85]
	global_load_dwordx4 v[148:151], v186, s[84:85] offset:1024
	global_load_dwordx4 v[152:155], v186, s[84:85] offset:2048
	global_load_dwordx4 v[156:159], v186, s[84:85] offset:3072
	s_waitcnt vmcnt(7)
	v_pk_add_f32 v[0:1], v[0:1], v[128:129]
	v_pk_add_f32 v[2:3], v[2:3], v[130:131]
	s_waitcnt vmcnt(6)
	v_pk_add_f32 v[4:5], v[4:5], v[132:133]
	v_pk_add_f32 v[6:7], v[6:7], v[134:135]
	s_waitcnt vmcnt(5)
	v_pk_add_f32 v[8:9], v[8:9], v[136:137]
	v_pk_add_f32 v[10:11], v[10:11], v[138:139]
	s_waitcnt vmcnt(4)
	v_pk_add_f32 v[12:13], v[12:13], v[140:141]
	v_pk_add_f32 v[14:15], v[14:15], v[142:143]
	s_waitcnt vmcnt(3)
	v_pk_add_f32 v[16:17], v[16:17], v[144:145]
	v_pk_add_f32 v[18:19], v[18:19], v[146:147]
	s_waitcnt vmcnt(2)
	v_pk_add_f32 v[20:21], v[20:21], v[148:149]
	v_pk_add_f32 v[22:23], v[22:23], v[150:151]
	s_waitcnt vmcnt(1)
	v_pk_add_f32 v[24:25], v[24:25], v[152:153]
	v_pk_add_f32 v[26:27], v[26:27], v[154:155]
	s_waitcnt vmcnt(0)
	v_pk_add_f32 v[28:29], v[28:29], v[156:157]
	v_pk_add_f32 v[30:31], v[30:31], v[158:159]
	s_add_u32 s84, s84, 0x1000
	s_addc_u32 s85, s85, 0
	global_load_dwordx4 v[128:131], v186, s[84:85]
	global_load_dwordx4 v[132:135], v186, s[84:85] offset:1024
	global_load_dwordx4 v[136:139], v186, s[84:85] offset:2048
	global_load_dwordx4 v[140:143], v186, s[84:85] offset:3072
	s_add_u32 s84, s84, 0x1000
	s_addc_u32 s85, s85, 0
	global_load_dwordx4 v[144:147], v186, s[84:85]
	global_load_dwordx4 v[148:151], v186, s[84:85] offset:1024
	global_load_dwordx4 v[152:155], v186, s[84:85] offset:2048
	global_load_dwordx4 v[156:159], v186, s[84:85] offset:3072
	s_waitcnt vmcnt(7)
	v_pk_add_f32 v[32:33], v[32:33], v[128:129]
	v_pk_add_f32 v[34:35], v[34:35], v[130:131]
	s_waitcnt vmcnt(6)
; template <class Epi, class Sched, bool ALIGN_EPI = false, bool SP2 = false>
; __device__ __forceinline__ void gemm_phase(PG8_LAS unsigned char* lds, const Gemm g, const Sched& S, const Epi& E) {
;     ...
;         if constexpr (!Epi::AFTER_DRAIN) { E(acc, cur, wr, wc, fr, fq); S.done(cur); }
	v_pk_add_f32 v[36:37], v[36:37], v[132:133]
	v_pk_add_f32 v[38:39], v[38:39], v[134:135]
	s_waitcnt vmcnt(5)
	v_pk_add_f32 v[40:41], v[40:41], v[136:137]
	v_pk_add_f32 v[42:43], v[42:43], v[138:139]
	s_waitcnt vmcnt(4)
	v_pk_add_f32 v[44:45], v[44:45], v[140:141]
	v_pk_add_f32 v[46:47], v[46:47], v[142:143]
	s_waitcnt vmcnt(3)
	v_pk_add_f32 v[48:49], v[48:49], v[144:145]
	v_pk_add_f32 v[50:51], v[50:51], v[146:147]
	s_waitcnt vmcnt(2)
	v_pk_add_f32 v[52:53], v[52:53], v[148:149]
	v_pk_add_f32 v[54:55], v[54:55], v[150:151]
	s_waitcnt vmcnt(1)
	v_pk_add_f32 v[56:57], v[56:57], v[152:153]
	v_pk_add_f32 v[58:59], v[58:59], v[154:155]
	s_waitcnt vmcnt(0)
	v_pk_add_f32 v[60:61], v[60:61], v[156:157]
	v_pk_add_f32 v[62:63], v[62:63], v[158:159]
	s_add_u32 s84, s84, 0x1000
	s_addc_u32 s85, s85, 0
	global_load_dwordx4 v[128:131], v186, s[84:85]
	global_load_dwordx4 v[132:135], v186, s[84:85] offset:1024
	global_load_dwordx4 v[136:139], v186, s[84:85] offset:2048
	global_load_dwordx4 v[140:143], v186, s[84:85] offset:3072
	s_add_u32 s84, s84, 0x1000
	s_addc_u32 s85, s85, 0
	global_load_dwordx4 v[144:147], v186, s[84:85]
	global_load_dwordx4 v[148:151], v186, s[84:85] offset:1024
	global_load_dwordx4 v[152:155], v186, s[84:85] offset:2048
	global_load_dwordx4 v[156:159], v186, s[84:85] offset:3072
	s_waitcnt vmcnt(7)
	v_pk_add_f32 v[64:65], v[64:65], v[128:129]
	v_pk_add_f32 v[66:67], v[66:67], v[130:131]
	s_waitcnt vmcnt(6)
	v_pk_add_f32 v[68:69], v[68:69], v[132:133]
	v_pk_add_f32 v[70:71], v[70:71], v[134:135]
	s_waitcnt vmcnt(5)
	v_pk_add_f32 v[72:73], v[72:73], v[136:137]
	v_pk_add_f32 v[74:75], v[74:75], v[138:139]
	s_waitcnt vmcnt(4)
	v_pk_add_f32 v[76:77], v[76:77], v[140:141]
	v_pk_add_f32 v[78:79], v[78:79], v[142:143]
	s_waitcnt vmcnt(3)
	v_pk_add_f32 v[80:81], v[80:81], v[144:145]
	v_pk_add_f32 v[82:83], v[82:83], v[146:147]
	s_waitcnt vmcnt(2)
	v_pk_add_f32 v[84:85], v[84:85], v[148:149]
	v_pk_add_f32 v[86:87], v[86:87], v[150:151]
	s_waitcnt vmcnt(1)
	v_pk_add_f32 v[88:89], v[88:89], v[152:153]
	v_pk_add_f32 v[90:91], v[90:91], v[154:155]
	s_waitcnt vmcnt(0)
	v_pk_add_f32 v[92:93], v[92:93], v[156:157]
	v_pk_add_f32 v[94:95], v[94:95], v[158:159]
	s_add_u32 s84, s84, 0x1000
	s_addc_u32 s85, s85, 0
	global_load_dwordx4 v[128:131], v186, s[84:85]
	global_load_dwordx4 v[132:135], v186, s[84:85] offset:1024
	global_load_dwordx4 v[136:139], v186, s[84:85] offset:2048
	global_load_dwordx4 v[140:143], v186, s[84:85] offset:3072
	s_add_u32 s84, s84, 0x1000
	s_addc_u32 s85, s85, 0
	global_load_dwordx4 v[144:147], v186, s[84:85]
	global_load_dwordx4 v[148:151], v186, s[84:85] offset:1024
	global_load_dwordx4 v[152:155], v186, s[84:85] offset:2048
	global_load_dwordx4 v[156:159], v186, s[84:85] offset:3072
	s_waitcnt vmcnt(7)
	v_pk_add_f32 v[96:97], v[96:97], v[128:129]
	v_pk_add_f32 v[98:99], v[98:99], v[130:131]
	s_waitcnt vmcnt(6)
	v_pk_add_f32 v[100:101], v[100:101], v[132:133]
	v_pk_add_f32 v[102:103], v[102:103], v[134:135]
	s_waitcnt vmcnt(5)
	v_pk_add_f32 v[104:105], v[104:105], v[136:137]
	v_pk_add_f32 v[106:107], v[106:107], v[138:139]
	s_waitcnt vmcnt(4)
	v_pk_add_f32 v[108:109], v[108:109], v[140:141]
	v_pk_add_f32 v[110:111], v[110:111], v[142:143]
	s_waitcnt vmcnt(3)
	v_pk_add_f32 v[112:113], v[112:113], v[144:145]
	v_pk_add_f32 v[114:115], v[114:115], v[146:147]
	s_waitcnt vmcnt(2)
	v_pk_add_f32 v[116:117], v[116:117], v[148:149]
	v_pk_add_f32 v[118:119], v[118:119], v[150:151]
	s_waitcnt vmcnt(1)
	v_pk_add_f32 v[120:121], v[120:121], v[152:153]
	v_pk_add_f32 v[122:123], v[122:123], v[154:155]
	s_waitcnt vmcnt(0)
	v_pk_add_f32 v[124:125], v[124:125], v[156:157]
	v_pk_add_f32 v[126:127], v[126:127], v[158:159]
	s_add_u32 s84, s84, 0x39000
	s_addc_u32 s85, s85, 0
	global_load_dwordx4 v[128:131], v186, s[84:85]
	global_load_dwordx4 v[132:135], v186, s[84:85] offset:1024
	global_load_dwordx4 v[136:139], v186, s[84:85] offset:2048
	global_load_dwordx4 v[140:143], v186, s[84:85] offset:3072
	s_add_u32 s84, s84, 0x1000
	s_addc_u32 s85, s85, 0
	global_load_dwordx4 v[144:147], v186, s[84:85]
	global_load_dwordx4 v[148:151], v186, s[84:85] offset:1024
	global_load_dwordx4 v[152:155], v186, s[84:85] offset:2048
	global_load_dwordx4 v[156:159], v186, s[84:85] offset:3072
	s_waitcnt vmcnt(7)
	v_pk_add_f32 v[0:1], v[0:1], v[128:129]
	v_pk_add_f32 v[2:3], v[2:3], v[130:131]
	s_waitcnt vmcnt(6)
	v_pk_add_f32 v[4:5], v[4:5], v[132:133]
	v_pk_add_f32 v[6:7], v[6:7], v[134:135]
	s_waitcnt vmcnt(5)
	v_pk_add_f32 v[8:9], v[8:9], v[136:137]
	v_pk_add_f32 v[10:11], v[10:11], v[138:139]
	s_waitcnt vmcnt(4)
	v_pk_add_f32 v[12:13], v[12:13], v[140:141]
	v_pk_add_f32 v[14:15], v[14:15], v[142:143]
	s_waitcnt vmcnt(3)
	v_pk_add_f32 v[16:17], v[16:17], v[144:145]
	v_pk_add_f32 v[18:19], v[18:19], v[146:147]
	s_waitcnt vmcnt(2)
	v_pk_add_f32 v[20:21], v[20:21], v[148:149]
	v_pk_add_f32 v[22:23], v[22:23], v[150:151]
	s_waitcnt vmcnt(1)
	v_pk_add_f32 v[24:25], v[24:25], v[152:153]
	v_pk_add_f32 v[26:27], v[26:27], v[154:155]
	s_waitcnt vmcnt(0)
	v_pk_add_f32 v[28:29], v[28:29], v[156:157]
	v_pk_add_f32 v[30:31], v[30:31], v[158:159]
	s_add_u32 s84, s84, 0x1000
	s_addc_u32 s85, s85, 0
	global_load_dwordx4 v[128:131], v186, s[84:85]
	global_load_dwordx4 v[132:135], v186, s[84:85] offset:1024
	global_load_dwordx4 v[136:139], v186, s[84:85] offset:2048
	global_load_dwordx4 v[140:143], v186, s[84:85] offset:3072
	s_add_u32 s84, s84, 0x1000
	s_addc_u32 s85, s85, 0
	global_load_dwordx4 v[144:147], v186, s[84:85]
	global_load_dwordx4 v[148:151], v186, s[84:85] offset:1024
	global_load_dwordx4 v[152:155], v186, s[84:85] offset:2048
	global_load_dwordx4 v[156:159], v186, s[84:85] offset:3072
	s_waitcnt vmcnt(7)
; template <class Epi, class Sched, bool ALIGN_EPI = false, bool SP2 = false>
; __device__ __forceinline__ void gemm_phase(PG8_LAS unsigned char* lds, const Gemm g, const Sched& S, const Epi& E) {
;     ...
;         if constexpr (!Epi::AFTER_DRAIN) { E(acc, cur, wr, wc, fr, fq); S.done(cur); }
	v_pk_add_f32 v[32:33], v[32:33], v[128:129]
	v_pk_add_f32 v[34:35], v[34:35], v[130:131]
	s_waitcnt vmcnt(6)
	v_pk_add_f32 v[36:37], v[36:37], v[132:133]
	v_pk_add_f32 v[38:39], v[38:39], v[134:135]
	s_waitcnt vmcnt(5)
	v_pk_add_f32 v[40:41], v[40:41], v[136:137]
	v_pk_add_f32 v[42:43], v[42:43], v[138:139]
	s_waitcnt vmcnt(4)
	v_pk_add_f32 v[44:45], v[44:45], v[140:141]
	v_pk_add_f32 v[46:47], v[46:47], v[142:143]
	s_waitcnt vmcnt(3)
	v_pk_add_f32 v[48:49], v[48:49], v[144:145]
	v_pk_add_f32 v[50:51], v[50:51], v[146:147]
	s_waitcnt vmcnt(2)
	v_pk_add_f32 v[52:53], v[52:53], v[148:149]
	v_pk_add_f32 v[54:55], v[54:55], v[150:151]
	s_waitcnt vmcnt(1)
	v_pk_add_f32 v[56:57], v[56:57], v[152:153]
	v_pk_add_f32 v[58:59], v[58:59], v[154:155]
	s_waitcnt vmcnt(0)
	v_pk_add_f32 v[60:61], v[60:61], v[156:157]
	v_pk_add_f32 v[62:63], v[62:63], v[158:159]
	s_add_u32 s84, s84, 0x1000
	s_addc_u32 s85, s85, 0
	global_load_dwordx4 v[128:131], v186, s[84:85]
	global_load_dwordx4 v[132:135], v186, s[84:85] offset:1024
	global_load_dwordx4 v[136:139], v186, s[84:85] offset:2048
	global_load_dwordx4 v[140:143], v186, s[84:85] offset:3072
	s_add_u32 s84, s84, 0x1000
	s_addc_u32 s85, s85, 0
	global_load_dwordx4 v[144:147], v186, s[84:85]
	global_load_dwordx4 v[148:151], v186, s[84:85] offset:1024
	global_load_dwordx4 v[152:155], v186, s[84:85] offset:2048
	global_load_dwordx4 v[156:159], v186, s[84:85] offset:3072
	s_waitcnt vmcnt(7)
	v_pk_add_f32 v[64:65], v[64:65], v[128:129]
	v_pk_add_f32 v[66:67], v[66:67], v[130:131]
	s_waitcnt vmcnt(6)
	v_pk_add_f32 v[68:69], v[68:69], v[132:133]
	v_pk_add_f32 v[70:71], v[70:71], v[134:135]
	s_waitcnt vmcnt(5)
	v_pk_add_f32 v[72:73], v[72:73], v[136:137]
	v_pk_add_f32 v[74:75], v[74:75], v[138:139]
	s_waitcnt vmcnt(4)
	v_pk_add_f32 v[76:77], v[76:77], v[140:141]
	v_pk_add_f32 v[78:79], v[78:79], v[142:143]
	s_waitcnt vmcnt(3)
	v_pk_add_f32 v[80:81], v[80:81], v[144:145]
	v_pk_add_f32 v[82:83], v[82:83], v[146:147]
	s_waitcnt vmcnt(2)
	v_pk_add_f32 v[84:85], v[84:85], v[148:149]
	v_pk_add_f32 v[86:87], v[86:87], v[150:151]
	s_waitcnt vmcnt(1)
	v_pk_add_f32 v[88:89], v[88:89], v[152:153]
	v_pk_add_f32 v[90:91], v[90:91], v[154:155]
	s_waitcnt vmcnt(0)
	v_pk_add_f32 v[92:93], v[92:93], v[156:157]
	v_pk_add_f32 v[94:95], v[94:95], v[158:159]
	s_add_u32 s84, s84, 0x1000
	s_addc_u32 s85, s85, 0
	global_load_dwordx4 v[128:131], v186, s[84:85]
	global_load_dwordx4 v[132:135], v186, s[84:85] offset:1024
	global_load_dwordx4 v[136:139], v186, s[84:85] offset:2048
	global_load_dwordx4 v[140:143], v186, s[84:85] offset:3072
	s_add_u32 s84, s84, 0x1000
	s_addc_u32 s85, s85, 0
	global_load_dwordx4 v[144:147], v186, s[84:85]
	global_load_dwordx4 v[148:151], v186, s[84:85] offset:1024
	global_load_dwordx4 v[152:155], v186, s[84:85] offset:2048
	global_load_dwordx4 v[156:159], v186, s[84:85] offset:3072
	s_waitcnt vmcnt(7)
	v_pk_add_f32 v[96:97], v[96:97], v[128:129]
	v_pk_add_f32 v[98:99], v[98:99], v[130:131]
	s_waitcnt vmcnt(6)
	v_pk_add_f32 v[100:101], v[100:101], v[132:133]
	v_pk_add_f32 v[102:103], v[102:103], v[134:135]
	s_waitcnt vmcnt(5)
	v_pk_add_f32 v[104:105], v[104:105], v[136:137]
	v_pk_add_f32 v[106:107], v[106:107], v[138:139]
	s_waitcnt vmcnt(4)
	v_pk_add_f32 v[108:109], v[108:109], v[140:141]
	v_pk_add_f32 v[110:111], v[110:111], v[142:143]
	s_waitcnt vmcnt(3)
	v_pk_add_f32 v[112:113], v[112:113], v[144:145]
	v_pk_add_f32 v[114:115], v[114:115], v[146:147]
	s_waitcnt vmcnt(2)
	v_pk_add_f32 v[116:117], v[116:117], v[148:149]
	v_pk_add_f32 v[118:119], v[118:119], v[150:151]
	s_waitcnt vmcnt(1)
	v_pk_add_f32 v[120:121], v[120:121], v[152:153]
	v_pk_add_f32 v[122:123], v[122:123], v[154:155]
	s_waitcnt vmcnt(0)
	v_pk_add_f32 v[124:125], v[124:125], v[156:157]
	v_pk_add_f32 v[126:127], v[126:127], v[158:159]
	s_add_u32 s84, s84, 0x39000
	s_addc_u32 s85, s85, 0
	global_load_dwordx4 v[128:131], v186, s[84:85]
	global_load_dwordx4 v[132:135], v186, s[84:85] offset:1024
	global_load_dwordx4 v[136:139], v186, s[84:85] offset:2048
	global_load_dwordx4 v[140:143], v186, s[84:85] offset:3072
	s_add_u32 s84, s84, 0x1000
	s_addc_u32 s85, s85, 0
	global_load_dwordx4 v[144:147], v186, s[84:85]
	global_load_dwordx4 v[148:151], v186, s[84:85] offset:1024
	global_load_dwordx4 v[152:155], v186, s[84:85] offset:2048
	global_load_dwordx4 v[156:159], v186, s[84:85] offset:3072
	s_waitcnt vmcnt(7)
	v_pk_add_f32 v[0:1], v[0:1], v[128:129]
	v_pk_add_f32 v[2:3], v[2:3], v[130:131]
	s_waitcnt vmcnt(6)
	v_pk_add_f32 v[4:5], v[4:5], v[132:133]
	v_pk_add_f32 v[6:7], v[6:7], v[134:135]
	s_waitcnt vmcnt(5)
	v_pk_add_f32 v[8:9], v[8:9], v[136:137]
	v_pk_add_f32 v[10:11], v[10:11], v[138:139]
	s_waitcnt vmcnt(4)
	v_pk_add_f32 v[12:13], v[12:13], v[140:141]
	v_pk_add_f32 v[14:15], v[14:15], v[142:143]
	s_waitcnt vmcnt(3)
; template <class Epi, class Sched, bool ALIGN_EPI = false, bool SP2 = false>
; __device__ __forceinline__ void gemm_phase(PG8_LAS unsigned char* lds, const Gemm g, const Sched& S, const Epi& E) {
;     ...
;         if constexpr (!Epi::AFTER_DRAIN) { E(acc, cur, wr, wc, fr, fq); S.done(cur); }
	v_pk_add_f32 v[16:17], v[16:17], v[144:145]
	v_pk_add_f32 v[18:19], v[18:19], v[146:147]
	s_waitcnt vmcnt(2)
	v_pk_add_f32 v[20:21], v[20:21], v[148:149]
	v_pk_add_f32 v[22:23], v[22:23], v[150:151]
	s_waitcnt vmcnt(1)
	v_pk_add_f32 v[24:25], v[24:25], v[152:153]
	v_pk_add_f32 v[26:27], v[26:27], v[154:155]
	s_waitcnt vmcnt(0)
	v_pk_add_f32 v[28:29], v[28:29], v[156:157]
	v_pk_add_f32 v[30:31], v[30:31], v[158:159]
	s_add_u32 s84, s84, 0x1000
	s_addc_u32 s85, s85, 0
	global_load_dwordx4 v[128:131], v186, s[84:85]
	global_load_dwordx4 v[132:135], v186, s[84:85] offset:1024
	global_load_dwordx4 v[136:139], v186, s[84:85] offset:2048
	global_load_dwordx4 v[140:143], v186, s[84:85] offset:3072
	s_add_u32 s84, s84, 0x1000
	s_addc_u32 s85, s85, 0
	global_load_dwordx4 v[144:147], v186, s[84:85]
	global_load_dwordx4 v[148:151], v186, s[84:85] offset:1024
	global_load_dwordx4 v[152:155], v186, s[84:85] offset:2048
	global_load_dwordx4 v[156:159], v186, s[84:85] offset:3072
	s_waitcnt vmcnt(7)
	v_pk_add_f32 v[32:33], v[32:33], v[128:129]
	v_pk_add_f32 v[34:35], v[34:35], v[130:131]
	s_waitcnt vmcnt(6)
	v_pk_add_f32 v[36:37], v[36:37], v[132:133]
	v_pk_add_f32 v[38:39], v[38:39], v[134:135]
	s_waitcnt vmcnt(5)
	v_pk_add_f32 v[40:41], v[40:41], v[136:137]
	v_pk_add_f32 v[42:43], v[42:43], v[138:139]
	s_waitcnt vmcnt(4)
	v_pk_add_f32 v[44:45], v[44:45], v[140:141]
	v_pk_add_f32 v[46:47], v[46:47], v[142:143]
	s_waitcnt vmcnt(3)
	v_pk_add_f32 v[48:49], v[48:49], v[144:145]
	v_pk_add_f32 v[50:51], v[50:51], v[146:147]
	s_waitcnt vmcnt(2)
	v_pk_add_f32 v[52:53], v[52:53], v[148:149]
	v_pk_add_f32 v[54:55], v[54:55], v[150:151]
	s_waitcnt vmcnt(1)
	v_pk_add_f32 v[56:57], v[56:57], v[152:153]
	v_pk_add_f32 v[58:59], v[58:59], v[154:155]
	s_waitcnt vmcnt(0)
	v_pk_add_f32 v[60:61], v[60:61], v[156:157]
	v_pk_add_f32 v[62:63], v[62:63], v[158:159]
	s_add_u32 s84, s84, 0x1000
	s_addc_u32 s85, s85, 0
	global_load_dwordx4 v[128:131], v186, s[84:85]
	global_load_dwordx4 v[132:135], v186, s[84:85] offset:1024
	global_load_dwordx4 v[136:139], v186, s[84:85] offset:2048
	global_load_dwordx4 v[140:143], v186, s[84:85] offset:3072
	s_add_u32 s84, s84, 0x1000
	s_addc_u32 s85, s85, 0
	global_load_dwordx4 v[144:147], v186, s[84:85]
	global_load_dwordx4 v[148:151], v186, s[84:85] offset:1024
	global_load_dwordx4 v[152:155], v186, s[84:85] offset:2048
	global_load_dwordx4 v[156:159], v186, s[84:85] offset:3072
	s_waitcnt vmcnt(7)
	v_pk_add_f32 v[64:65], v[64:65], v[128:129]
	v_pk_add_f32 v[66:67], v[66:67], v[130:131]
	s_waitcnt vmcnt(6)
	v_pk_add_f32 v[68:69], v[68:69], v[132:133]
	v_pk_add_f32 v[70:71], v[70:71], v[134:135]
	s_waitcnt vmcnt(5)
	v_pk_add_f32 v[72:73], v[72:73], v[136:137]
	v_pk_add_f32 v[74:75], v[74:75], v[138:139]
	s_waitcnt vmcnt(4)
	v_pk_add_f32 v[76:77], v[76:77], v[140:141]
	v_pk_add_f32 v[78:79], v[78:79], v[142:143]
	s_waitcnt vmcnt(3)
	v_pk_add_f32 v[80:81], v[80:81], v[144:145]
	v_pk_add_f32 v[82:83], v[82:83], v[146:147]
	s_waitcnt vmcnt(2)
	v_pk_add_f32 v[84:85], v[84:85], v[148:149]
	v_pk_add_f32 v[86:87], v[86:87], v[150:151]
	s_waitcnt vmcnt(1)
	v_pk_add_f32 v[88:89], v[88:89], v[152:153]
	v_pk_add_f32 v[90:91], v[90:91], v[154:155]
	s_waitcnt vmcnt(0)
	v_pk_add_f32 v[92:93], v[92:93], v[156:157]
	v_pk_add_f32 v[94:95], v[94:95], v[158:159]
	s_add_u32 s84, s84, 0x1000
	s_addc_u32 s85, s85, 0
	global_load_dwordx4 v[128:131], v186, s[84:85]
	global_load_dwordx4 v[132:135], v186, s[84:85] offset:1024
	global_load_dwordx4 v[136:139], v186, s[84:85] offset:2048
	global_load_dwordx4 v[140:143], v186, s[84:85] offset:3072
	s_add_u32 s84, s84, 0x1000
	s_addc_u32 s85, s85, 0
	global_load_dwordx4 v[144:147], v186, s[84:85]
	global_load_dwordx4 v[148:151], v186, s[84:85] offset:1024
	global_load_dwordx4 v[152:155], v186, s[84:85] offset:2048
	global_load_dwordx4 v[156:159], v186, s[84:85] offset:3072
	s_waitcnt vmcnt(7)
	v_pk_add_f32 v[96:97], v[96:97], v[128:129]
	v_pk_add_f32 v[98:99], v[98:99], v[130:131]
	s_waitcnt vmcnt(6)
	v_pk_add_f32 v[100:101], v[100:101], v[132:133]
	v_pk_add_f32 v[102:103], v[102:103], v[134:135]
	s_waitcnt vmcnt(5)
	v_pk_add_f32 v[104:105], v[104:105], v[136:137]
	v_pk_add_f32 v[106:107], v[106:107], v[138:139]
	s_waitcnt vmcnt(4)
	v_pk_add_f32 v[108:109], v[108:109], v[140:141]
	v_pk_add_f32 v[110:111], v[110:111], v[142:143]
	s_waitcnt vmcnt(3)
	v_pk_add_f32 v[112:113], v[112:113], v[144:145]
	v_pk_add_f32 v[114:115], v[114:115], v[146:147]
	s_waitcnt vmcnt(2)
	v_pk_add_f32 v[116:117], v[116:117], v[148:149]
	v_pk_add_f32 v[118:119], v[118:119], v[150:151]
	s_waitcnt vmcnt(1)
	v_pk_add_f32 v[120:121], v[120:121], v[152:153]
	v_pk_add_f32 v[122:123], v[122:123], v[154:155]
	s_waitcnt vmcnt(0)
	v_pk_add_f32 v[124:125], v[124:125], v[156:157]
	v_pk_add_f32 v[126:127], v[126:127], v[158:159]

; #define LAS __attribute__((address_space(3)))
; DI void p0_prologue(const Args& a, LAS unsigned char* lds, int tid, int wave, int lane, bool first) {
;     ...
;     LAS float* scr = (LAS float*)(lds + wave * 16384);
;     const int gw = blockIdx.x * 8 + wave, NGW = gridDim.x * 8;
;     constexpr int I_UP = (D / 64) * (NUP / 32), I_DN = (FF / 64) * (D / 32), I_IN = (D / 64) * (NIN / 32), I_OUT = (D / 64) * (D / 32);
;     constexpr int NITEMS = 2 * I_UP + 2 * I_DN + I_IN + I_OUT;
;     for (int it = gw; it < NITEMS; it += NGW) {
.LBB0_648:
	s_cmp_lg_u32 s77, 3
	s_cbranch_scc1 .Lno_tail
	v_readlane_b32 s92, v255, 31
	v_readlane_b32 s4, v255, 18
	s_cmpk_lg_i32 s92, 0x100
	s_cbranch_scc1 .Lno_tail
	s_cmpk_lt_u32 s4, 0x80
	s_cbranch_scc1 .Lno_tail
	v_readlane_b32 s8, v255, 49
	s_lshl_b32 s4, s4, 3
	s_add_i32 s100, s4, s8
	s_addk_i32 s100, 0xfc00
	s_movk_i32 s101, 0x400
	s_waitcnt vmcnt(0) lgkmcnt(0)
	v_mov_b32_e32 v172, v194
	v_mov_b32_e32 v161, 0
	v_and_b32_e32 v207, 63, v172
	v_readlane_b32 s34, v255, 43
	v_readlane_b32 s38, v255, 21
	v_readlane_b32 s39, v255, 22
	v_readlane_b32 s40, v255, 23
	v_readlane_b32 s41, v255, 24
	v_readlane_b32 s42, v255, 25
	v_readlane_b32 s43, v255, 26
	v_readlane_b32 s90, v255, 29
	v_readlane_b32 s91, v255, 30
	s_mov_b32 s36, 0x800000
	s_mov_b32 s53, 0
	s_movk_i32 s79, 0x84
	s_movk_i32 s73, 0x3800
	s_movk_i32 s76, 0x5800
	s_branch .Ltr_setup
